# diff-attention epilogue: sub-layernorm gain loads prefetched together at epilogue start
# baseline (speedup 1.0000x reference)
; DI float bf_lo(unsigned w) { return __uint_as_float(w << 16); }
; DI float bf_hi(unsigned w) { return __uint_as_float(w & 0xffff0000u); }
; DI void phase_attention(KParams P, LAS unsigned char* lds) {
;     ...
;       float ss = 0.f;
; #pragma unroll
;       for (int i = 0; i < 4; ++i)
; #pragma unroll
;         for (int j = 0; j < 8; ++j) { const float a = bf_lo(o1p[i][j]) - lam * O[i][2 * j], c = bf_hi(o1p[i][j]) - lam * O[i][2 * j + 1]; O[i][2 * j] = a; O[i][2 * j + 1] = c; ss += a * a + c * c; }
;       ss += __shfl_xor(ss, 32);
;       const float rs = rsqrtf(ss * (1.f / 128.f) + 1e-5f) * 0.8f;
; #pragma unroll
;       for (int i = 0; i < 4; ++i)
; #pragma unroll
;         for (int g = 0; g < 4; ++g) { const f32x4 gn = *(const f32x4*)(P->subln + 32 * i + 8 * g + 4 * h);
; #pragma unroll
;           for (int e = 0; e < 4; ++e) O[i][4 * g + e] *= rs * gn[e]; }
.LBB0_96:
	s_load_dwordx2 s[10:11], s[0:1], 0x50
	v_lshlrev_b32_e32 v92, 2, v150
	s_waitcnt lgkmcnt(0)
	global_load_dwordx4 v[96:99], v92, s[10:11]
	global_load_dwordx4 v[100:103], v92, s[10:11] offset:32
	global_load_dwordx4 v[104:107], v92, s[10:11] offset:64
	global_load_dwordx4 v[108:111], v92, s[10:11] offset:96
	global_load_dwordx4 v[112:115], v92, s[10:11] offset:128
	global_load_dwordx4 v[116:119], v92, s[10:11] offset:160
	global_load_dwordx4 v[120:123], v92, s[10:11] offset:192
	global_load_dwordx4 v[124:127], v92, s[10:11] offset:224
	global_load_dwordx4 v[128:131], v92, s[10:11] offset:256
	global_load_dwordx4 v[132:135], v92, s[10:11] offset:288
	global_load_dwordx4 v[136:139], v92, s[10:11] offset:320
	global_load_dwordx4 v[140:143], v92, s[10:11] offset:352
	global_load_dwordx4 v[230:233], v92, s[10:11] offset:384
	global_load_dwordx4 v[234:237], v92, s[10:11] offset:416
	global_load_dwordx4 v[238:241], v92, s[10:11] offset:448
	global_load_dwordx4 v[242:245], v92, s[10:11] offset:480
	v_lshlrev_b32_e32 v24, 16, v172
	v_fma_f32 v0, -v148, v0, v24
	v_and_b32_e32 v24, 0xffff0000, v172
	v_and_b32_e32 v26, 0xffff0000, v173
	v_fma_f32 v24, -v148, v91, v24
	v_lshlrev_b32_e32 v25, 16, v173
	v_fma_f32 v26, -v148, v89, v26
	v_mul_f32_e32 v27, v24, v24
	v_fma_f32 v25, -v148, v90, v25
	v_mul_f32_e32 v28, v26, v26
	v_fmac_f32_e32 v27, v0, v0
	v_fmac_f32_e32 v28, v25, v25
	v_add_f32_e32 v29, v28, v27
	v_and_b32_e32 v28, 0xffff0000, v174
	v_lshlrev_b32_e32 v27, 16, v174
	v_fma_f32 v28, -v148, v87, v28
	v_fma_f32 v27, -v148, v88, v27
	v_mul_f32_e32 v30, v28, v28
	v_fmac_f32_e32 v30, v27, v27
	v_add_f32_e32 v31, v30, v29
	v_and_b32_e32 v30, 0xffff0000, v175
	v_lshlrev_b32_e32 v29, 16, v175
	v_fma_f32 v30, -v148, v85, v30
	v_fma_f32 v29, -v148, v86, v29
	v_mul_f32_e32 v32, v30, v30
	v_fmac_f32_e32 v32, v29, v29
	v_add_f32_e32 v33, v32, v31
	v_and_b32_e32 v32, 0xffff0000, v176
	v_lshlrev_b32_e32 v31, 16, v176
	v_fma_f32 v32, -v148, v83, v32
	v_fma_f32 v31, -v148, v84, v31
	v_mul_f32_e32 v34, v32, v32
	v_fmac_f32_e32 v34, v31, v31
	v_add_f32_e32 v35, v34, v33
	v_and_b32_e32 v34, 0xffff0000, v177
	v_lshlrev_b32_e32 v33, 16, v177
	v_fma_f32 v34, -v148, v81, v34
	v_fma_f32 v33, -v148, v82, v33
	v_mul_f32_e32 v36, v34, v34
	v_fmac_f32_e32 v36, v33, v33
	v_add_f32_e32 v40, v36, v35
	v_and_b32_e32 v36, 0xffff0000, v178
	v_lshlrev_b32_e32 v35, 16, v178
	v_fma_f32 v36, -v148, v77, v36
	v_fma_f32 v35, -v148, v80, v35
	v_mul_f32_e32 v41, v36, v36
	v_fmac_f32_e32 v41, v35, v35
	v_add_f32_e32 v40, v41, v40
	v_lshlrev_b32_e32 v41, 16, v179
	v_fma_f32 v42, -v148, v76, v41
	v_and_b32_e32 v41, 0xffff0000, v179
	v_fma_f32 v43, -v148, v75, v41
	v_mul_f32_e32 v41, v43, v43
	v_fmac_f32_e32 v41, v42, v42
	v_add_f32_e32 v40, v41, v40
	v_lshlrev_b32_e32 v41, 16, v180
	v_fma_f32 v44, -v148, v74, v41
	v_and_b32_e32 v41, 0xffff0000, v180
	v_fma_f32 v45, -v148, v73, v41
	v_mul_f32_e32 v41, v45, v45
	v_fmac_f32_e32 v41, v44, v44
	v_add_f32_e32 v40, v41, v40
	v_lshlrev_b32_e32 v41, 16, v181
	v_fma_f32 v46, -v148, v72, v41
	v_and_b32_e32 v41, 0xffff0000, v181
	v_fma_f32 v47, -v148, v71, v41
	v_mul_f32_e32 v41, v47, v47
	v_fmac_f32_e32 v41, v46, v46
	v_add_f32_e32 v40, v41, v40
	v_lshlrev_b32_e32 v41, 16, v182
	v_fma_f32 v60, -v148, v70, v41
	v_and_b32_e32 v41, 0xffff0000, v182
	v_fma_f32 v61, -v148, v69, v41
	v_mul_f32_e32 v41, v61, v61
	v_fmac_f32_e32 v41, v60, v60
	v_add_f32_e32 v40, v41, v40
	v_lshlrev_b32_e32 v41, 16, v183
	v_fma_f32 v62, -v148, v68, v41
	v_and_b32_e32 v41, 0xffff0000, v183
	v_fma_f32 v63, -v148, v67, v41
	v_mul_f32_e32 v41, v63, v63
	v_fmac_f32_e32 v41, v62, v62
	v_add_f32_e32 v40, v41, v40
	v_lshlrev_b32_e32 v41, 16, v184
	v_fma_f32 v66, -v148, v66, v41
	v_and_b32_e32 v41, 0xffff0000, v184
	v_fma_f32 v65, -v148, v65, v41
	v_mul_f32_e32 v41, v65, v65
	v_fmac_f32_e32 v41, v66, v66
	v_add_f32_e32 v40, v41, v40
	v_lshlrev_b32_e32 v41, 16, v185
	v_fma_f32 v64, -v148, v64, v41
	v_and_b32_e32 v41, 0xffff0000, v185
	v_fma_f32 v59, -v148, v59, v41
	v_mul_f32_e32 v41, v59, v59
	v_fmac_f32_e32 v41, v64, v64
	v_add_f32_e32 v40, v41, v40
	v_lshlrev_b32_e32 v41, 16, v204
	v_fma_f32 v58, -v148, v58, v41
	v_and_b32_e32 v41, 0xffff0000, v204
	v_fma_f32 v57, -v148, v57, v41
	v_mul_f32_e32 v41, v57, v57
	v_fmac_f32_e32 v41, v58, v58
	v_add_f32_e32 v40, v41, v40
	v_lshlrev_b32_e32 v41, 16, v205
	v_fma_f32 v56, -v148, v56, v41
	v_and_b32_e32 v41, 0xffff0000, v205
	v_fma_f32 v55, -v148, v55, v41
	v_mul_f32_e32 v41, v55, v55
	v_fmac_f32_e32 v41, v56, v56
	v_add_f32_e32 v40, v41, v40
	v_lshlrev_b32_e32 v41, 16, v206
	v_fma_f32 v67, -v148, v54, v41
	v_and_b32_e32 v41, 0xffff0000, v206
	v_fma_f32 v68, -v148, v53, v41
	v_mul_f32_e32 v41, v68, v68
	v_fmac_f32_e32 v41, v67, v67
	v_add_f32_e32 v40, v41, v40
	v_lshlrev_b32_e32 v41, 16, v207
	v_fma_f32 v69, -v148, v52, v41
	v_and_b32_e32 v41, 0xffff0000, v207
	v_fma_f32 v70, -v148, v51, v41
	v_mul_f32_e32 v41, v70, v70
	v_fmac_f32_e32 v41, v69, v69
	v_add_f32_e32 v40, v41, v40
	v_lshlrev_b32_e32 v41, 16, v208
	v_fma_f32 v71, -v148, v50, v41
	v_and_b32_e32 v41, 0xffff0000, v208
	v_fma_f32 v72, -v148, v49, v41
	v_mul_f32_e32 v41, v72, v72
	v_fmac_f32_e32 v41, v71, v71
	v_add_f32_e32 v40, v41, v40
	v_lshlrev_b32_e32 v41, 16, v209
	v_fma_f32 v73, -v148, v48, v41
	v_and_b32_e32 v41, 0xffff0000, v209
	v_fma_f32 v74, -v148, v39, v41
	v_mul_f32_e32 v39, v74, v74
	v_fmac_f32_e32 v39, v73, v73
	v_add_f32_e32 v39, v39, v40
	v_lshlrev_b32_e32 v40, 16, v210
	v_fma_f32 v75, -v148, v38, v40
	v_and_b32_e32 v38, 0xffff0000, v210
	v_fma_f32 v76, -v148, v37, v38
	v_lshlrev_b32_e32 v38, 16, v211
	v_fma_f32 v77, -v148, v5, v38
	v_and_b32_e32 v5, 0xffff0000, v211
; DI float bf_lo(unsigned w) { return __uint_as_float(w << 16); }
; DI float bf_hi(unsigned w) { return __uint_as_float(w & 0xffff0000u); }
; DI void phase_attention(KParams P, LAS unsigned char* lds) {
;     ...
;       for (int i = 0; i < 4; ++i)
; #pragma unroll
;         for (int j = 0; j < 8; ++j) { const float a = bf_lo(o1p[i][j]) - lam * O[i][2 * j], c = bf_hi(o1p[i][j]) - lam * O[i][2 * j + 1]; O[i][2 * j] = a; O[i][2 * j + 1] = c; ss += a * a + c * c; }
;       ss += __shfl_xor(ss, 32);
;       const float rs = rsqrtf(ss * (1.f / 128.f) + 1e-5f) * 0.8f;
; #pragma unroll
;       for (int i = 0; i < 4; ++i)
; #pragma unroll
;         for (int g = 0; g < 4; ++g) { const f32x4 gn = *(const f32x4*)(P->subln + 32 * i + 8 * g + 4 * h);
; #pragma unroll
;           for (int e = 0; e < 4; ++e) O[i][4 * g + e] *= rs * gn[e]; }
	v_mul_f32_e32 v37, v76, v76
	v_fma_f32 v78, -v148, v4, v5
	v_fmac_f32_e32 v37, v75, v75
	v_mul_f32_e32 v4, v78, v78
	v_add_f32_e32 v37, v37, v39
	v_fmac_f32_e32 v4, v77, v77
	v_add_f32_e32 v37, v4, v37
	v_lshlrev_b32_e32 v5, 16, v153
	v_lshlrev_b32_e32 v4, 16, v152
	v_and_b32_e32 v39, 0xffff0000, v153
	v_and_b32_e32 v38, 0xffff0000, v152
	v_pk_fma_f32 v[4:5], v[148:149], v[2:3], v[4:5] neg_lo:[1,0,0] neg_hi:[1,0,0]
	v_pk_fma_f32 v[2:3], v[148:149], v[8:9], v[38:39] neg_lo:[1,0,0] neg_hi:[1,0,0]
	v_and_b32_e32 v39, 0xffff0000, v155
	v_pk_mul_f32 v[8:9], v[2:3], v[2:3]
	v_and_b32_e32 v38, 0xffff0000, v154
	v_pk_fma_f32 v[8:9], v[4:5], v[4:5], v[8:9]
	s_load_dwordx2 s[10:11], s[0:1], 0x50
	v_add_f32_e32 v9, v9, v37
	v_add_f32_e32 v37, v8, v9
	v_lshlrev_b32_e32 v9, 16, v155
	v_lshlrev_b32_e32 v8, 16, v154
	v_pk_fma_f32 v[8:9], v[148:149], v[6:7], v[8:9] neg_lo:[1,0,0] neg_hi:[1,0,0]
	v_pk_fma_f32 v[6:7], v[148:149], v[12:13], v[38:39] neg_lo:[1,0,0] neg_hi:[1,0,0]
	v_and_b32_e32 v39, 0xffff0000, v157
	v_pk_mul_f32 v[12:13], v[6:7], v[6:7]
	v_and_b32_e32 v38, 0xffff0000, v156
	v_pk_fma_f32 v[12:13], v[8:9], v[8:9], v[12:13]
	v_lshlrev_b32_e32 v80, 2, v150
	v_add_f32_e32 v13, v13, v37
	v_add_f32_e32 v37, v12, v13
	v_lshlrev_b32_e32 v13, 16, v157
	v_lshlrev_b32_e32 v12, 16, v156
	v_pk_fma_f32 v[12:13], v[148:149], v[10:11], v[12:13] neg_lo:[1,0,0] neg_hi:[1,0,0]
	v_pk_fma_f32 v[10:11], v[148:149], v[16:17], v[38:39] neg_lo:[1,0,0] neg_hi:[1,0,0]
	v_and_b32_e32 v39, 0xffff0000, v159
	v_pk_mul_f32 v[16:17], v[10:11], v[10:11]
	v_and_b32_e32 v38, 0xffff0000, v158
	v_pk_fma_f32 v[16:17], v[12:13], v[12:13], v[16:17]
	s_waitcnt lgkmcnt(0)
	s_waitcnt vmcnt(0)
	v_mov_b32_e32 v50, v124
	v_mov_b32_e32 v51, v125
	v_mov_b32_e32 v52, v126
	v_mov_b32_e32 v53, v127
	v_add_f32_e32 v17, v17, v37
	v_add_f32_e32 v37, v16, v17
	v_lshlrev_b32_e32 v17, 16, v159
	v_lshlrev_b32_e32 v16, 16, v158
	v_pk_fma_f32 v[16:17], v[148:149], v[14:15], v[16:17] neg_lo:[1,0,0] neg_hi:[1,0,0]
	v_pk_fma_f32 v[14:15], v[148:149], v[20:21], v[38:39] neg_lo:[1,0,0] neg_hi:[1,0,0]
	v_and_b32_e32 v39, 0xffff0000, v161
	v_pk_mul_f32 v[20:21], v[14:15], v[14:15]
	v_and_b32_e32 v38, 0xffff0000, v160
	v_pk_fma_f32 v[20:21], v[16:17], v[16:17], v[20:21]
	v_lshlrev_b32_e32 v166, 1, v150
	v_add_f32_e32 v21, v21, v37
	v_add_f32_e32 v37, v20, v21
	v_lshlrev_b32_e32 v21, 16, v161
	v_lshlrev_b32_e32 v20, 16, v160
	v_pk_fma_f32 v[20:21], v[148:149], v[18:19], v[20:21] neg_lo:[1,0,0] neg_hi:[1,0,0]
	v_pk_fma_f32 v[18:19], v[148:149], v[22:23], v[38:39] neg_lo:[1,0,0] neg_hi:[1,0,0]
	v_mov_b32_e32 v38, v96
	v_mov_b32_e32 v39, v97
	v_mov_b32_e32 v40, v98
	v_mov_b32_e32 v41, v99
	v_pk_mul_f32 v[22:23], v[18:19], v[18:19]
	v_mov_b32_e32 v167, v1
	v_pk_fma_f32 v[22:23], v[20:21], v[20:21], v[22:23]
	s_nop 0
	v_add_f32_e32 v23, v23, v37
	v_add_f32_e32 v22, v22, v23
	ds_bpermute_b32 v23, v151, v22
	s_waitcnt lgkmcnt(0)
	v_add_f32_e32 v22, v22, v23
	v_fmamk_f32 v22, v22, 0x3c000000, v186
	v_cmp_gt_f32_e32 vcc, s2, v22
	v_mul_f32_e32 v23, 0x4b800000, v22
	s_nop 0
	v_cndmask_b32_e32 v22, v22, v23, vcc
	v_rsq_f32_e32 v22, v22
	s_nop 0
	v_mul_f32_e32 v23, 0x45800000, v22
	v_cndmask_b32_e32 v22, v22, v23, vcc
	v_mul_f32_e32 v79, 0x3f4ccccd, v22
	s_waitcnt vmcnt(0)
	v_mul_f32_e32 v22, v38, v79
	v_mul_f32_e32 v0, v0, v22
	v_mul_f32_e32 v22, v39, v79
	v_mul_f32_e32 v22, v24, v22
	v_mul_f32_e32 v23, v40, v79
	v_mul_f32_e32 v24, v41, v79
	v_mov_b32_e32 v38, v100
	v_mov_b32_e32 v39, v101
	v_mov_b32_e32 v40, v102
	v_mov_b32_e32 v41, v103
	v_mul_f32_e32 v23, v25, v23
	v_mul_f32_e32 v25, v26, v24
	s_waitcnt vmcnt(0)
	v_mul_f32_e32 v24, v38, v79
	v_mul_f32_e32 v26, v39, v79
	v_mul_f32_e32 v24, v27, v24
	v_mul_f32_e32 v26, v28, v26
	v_mul_f32_e32 v27, v40, v79
	v_mul_f32_e32 v28, v41, v79
	v_mov_b32_e32 v38, v104
	v_mov_b32_e32 v39, v105
	v_mov_b32_e32 v40, v106
	v_mov_b32_e32 v41, v107
	v_mul_f32_e32 v27, v29, v27
	v_mul_f32_e32 v29, v30, v28
	s_waitcnt vmcnt(0)
	v_mul_f32_e32 v28, v38, v79
	v_mul_f32_e32 v30, v39, v79
	v_mul_f32_e32 v28, v31, v28
	v_mul_f32_e32 v30, v32, v30
	v_mul_f32_e32 v31, v40, v79
	v_mul_f32_e32 v32, v41, v79
	v_mov_b32_e32 v38, v108
	v_mov_b32_e32 v39, v109
	v_mov_b32_e32 v40, v110
	v_mov_b32_e32 v41, v111
	v_mul_f32_e32 v31, v33, v31
	v_mul_f32_e32 v33, v34, v32
	s_waitcnt vmcnt(0)
	v_mul_f32_e32 v32, v38, v79
	v_mul_f32_e32 v34, v39, v79
	v_mul_f32_e32 v32, v35, v32
	v_mul_f32_e32 v34, v36, v34
	v_mul_f32_e32 v35, v40, v79
	v_mul_f32_e32 v36, v41, v79
	v_mov_b32_e32 v38, v112
	v_mov_b32_e32 v39, v113
	v_mov_b32_e32 v40, v114
	v_mov_b32_e32 v41, v115
	v_mul_f32_e32 v37, v43, v36
	v_mul_f32_e32 v35, v42, v35
	s_waitcnt vmcnt(0)
	v_mul_f32_e32 v36, v38, v79
	v_mul_f32_e32 v38, v39, v79
	v_mul_f32_e32 v36, v44, v36
	v_mul_f32_e32 v38, v45, v38
	v_mul_f32_e32 v39, v40, v79
	v_mul_f32_e32 v40, v41, v79
	v_mov_b32_e32 v42, v116
	v_mov_b32_e32 v43, v117
	v_mov_b32_e32 v44, v118
	v_mov_b32_e32 v45, v119
	v_mul_f32_e32 v39, v46, v39
	v_mul_f32_e32 v41, v47, v40
	v_mov_b32_e32 v46, v120
	v_mov_b32_e32 v47, v121
	v_mov_b32_e32 v48, v122
	v_mov_b32_e32 v49, v123
	s_waitcnt vmcnt(1)
	v_mul_f32_e32 v40, v42, v79
	v_mul_f32_e32 v42, v43, v79
	v_mul_f32_e32 v43, v44, v79
	v_mul_f32_e32 v44, v45, v79
	v_mul_f32_e32 v45, v63, v44
	s_waitcnt vmcnt(0)
; DI unsigned cvt_pk_bf16(float lo, float hi) { unsigned r; asm volatile("v_cvt_pk_bf16_f32 %0, %1, %2" : "=v"(r) : "v"(lo), "v"(hi)); return r; }
; DI void attn_store(const f32x16 (&O)[4], bf16_t* dst, int qrow, int h) {
; #pragma unroll
;   for (int vt = 0; vt < 4; ++vt)
; #pragma unroll
;     for (int g = 0; g < 4; ++g) {
;       u32x2 w; w.x = cvt_pk_bf16(O[vt][4 * g], O[vt][4 * g + 1]); w.y = cvt_pk_bf16(O[vt][4 * g + 2], O[vt][4 * g + 3]);
;       *(u32x2*)(dst + (size_t)qrow * DM + 32 * vt + 8 * g + 4 * h) = w;
;     }
; }
; DI void phase_attention(KParams P, LAS unsigned char* lds) {
;     ...
; #pragma unroll
;       for (int i = 0; i < 4; ++i)
; #pragma unroll
;         for (int g = 0; g < 4; ++g) { const f32x4 gn = *(const f32x4*)(P->subln + 32 * i + 8 * g + 4 * h);
; #pragma unroll
;           for (int e = 0; e < 4; ++e) O[i][4 * g + e] *= rs * gn[e]; }
;       attn_store(O, P->act + rb * DM + head * 128, q0 + wid * 32 + r, h);
	v_mul_f32_e32 v44, v46, v79
	v_mul_f32_e32 v46, v47, v79
	v_mul_f32_e32 v47, v48, v79
	v_mul_f32_e32 v48, v49, v79
	v_mul_f32_e32 v49, v59, v48
	v_mul_f32_e32 v48, v79, v50
	v_mul_f32_e32 v50, v79, v51
	v_mul_f32_e32 v51, v79, v52
	v_mul_f32_e32 v52, v79, v53
	v_mul_f32_e32 v50, v57, v50
	v_mul_f32_e32 v51, v56, v51
	v_mul_f32_e32 v53, v55, v52
	v_mov_b32_e32 v54, v128
	v_mov_b32_e32 v55, v129
	v_mov_b32_e32 v56, v130
	v_mov_b32_e32 v57, v131
	v_mul_f32_e32 v40, v60, v40
	v_mul_f32_e32 v42, v61, v42
	v_mul_f32_e32 v48, v58, v48
	v_mov_b32_e32 v58, v132
	v_mov_b32_e32 v59, v133
	v_mov_b32_e32 v60, v134
	v_mov_b32_e32 v61, v135
	v_mul_f32_e32 v43, v62, v43
	v_mul_f32_e32 v44, v66, v44
	v_mul_f32_e32 v46, v65, v46
	v_mul_f32_e32 v47, v64, v47
	v_mov_b32_e32 v62, v136
	v_mov_b32_e32 v63, v137
	v_mov_b32_e32 v64, v138
	v_mov_b32_e32 v65, v139
	s_waitcnt vmcnt(2)
	v_mul_f32_e32 v52, v79, v54
	v_mul_f32_e32 v54, v79, v55
	v_mul_f32_e32 v55, v79, v56
	v_mul_f32_e32 v52, v67, v52
	v_mul_f32_e32 v54, v68, v54
	v_mul_f32_e32 v55, v69, v55
	v_mov_b32_e32 v66, v140
	v_mov_b32_e32 v67, v141
	v_mov_b32_e32 v68, v142
	v_mov_b32_e32 v69, v143
	v_mul_f32_e32 v56, v79, v57
	v_mul_f32_e32 v57, v70, v56
	s_waitcnt vmcnt(2)
	v_mul_f32_e32 v56, v79, v58
	v_mul_f32_e32 v58, v79, v59
	v_mul_f32_e32 v59, v79, v60
	v_mul_f32_e32 v60, v79, v61
	v_mul_f32_e32 v61, v74, v60
	s_waitcnt vmcnt(1)
	v_mul_f32_e32 v60, v79, v62
	v_mul_f32_e32 v62, v79, v63
	v_mul_f32_e32 v63, v79, v64
	v_mul_f32_e32 v64, v79, v65
	v_mul_f32_e32 v56, v71, v56
	v_mul_f32_e32 v58, v72, v58
	v_mul_f32_e32 v59, v73, v59
	v_mul_f32_e32 v60, v75, v60
	v_mul_f32_e32 v62, v76, v62
	v_mul_f32_e32 v63, v77, v63
	v_mul_f32_e32 v64, v78, v64
	s_waitcnt vmcnt(0)
	v_mul_f32_e32 v65, v79, v66
	v_mul_f32_e32 v5, v5, v65
	v_mul_f32_e32 v65, v79, v67
	v_mul_f32_e32 v3, v3, v65
	v_mul_f32_e32 v65, v79, v68
	v_mul_f32_e32 v4, v4, v65
	v_mul_f32_e32 v65, v79, v69
	v_mov_b32_e32 v66, v230
	v_mov_b32_e32 v67, v231
	v_mov_b32_e32 v68, v232
	v_mov_b32_e32 v69, v233
	v_mul_f32_e32 v65, v2, v65
	s_waitcnt vmcnt(0)
	v_mul_f32_e32 v2, v79, v66
	v_mul_f32_e32 v2, v9, v2
	v_mul_f32_e32 v9, v79, v67
	v_mul_f32_e32 v7, v7, v9
	v_mul_f32_e32 v9, v79, v68
	v_mul_f32_e32 v8, v8, v9
	v_mul_f32_e32 v9, v79, v69
	v_mov_b32_e32 v66, v234
	v_mov_b32_e32 v67, v235
	v_mov_b32_e32 v68, v236
	v_mov_b32_e32 v69, v237
	v_mul_f32_e32 v9, v6, v9
	s_waitcnt vmcnt(0)
	v_mul_f32_e32 v6, v79, v66
	v_mul_f32_e32 v6, v13, v6
	v_mul_f32_e32 v13, v79, v67
	v_mul_f32_e32 v11, v11, v13
	v_mul_f32_e32 v13, v79, v68
	v_mul_f32_e32 v12, v12, v13
	v_mul_f32_e32 v13, v79, v69
	v_mov_b32_e32 v66, v238
	v_mov_b32_e32 v67, v239
	v_mov_b32_e32 v68, v240
	v_mov_b32_e32 v69, v241
	v_mul_f32_e32 v13, v10, v13
	s_waitcnt vmcnt(0)
	v_mul_f32_e32 v10, v79, v66
	v_mul_f32_e32 v10, v17, v10
	v_mul_f32_e32 v17, v79, v67
	v_mul_f32_e32 v15, v15, v17
	v_mul_f32_e32 v17, v79, v68
	v_mul_f32_e32 v16, v16, v17
	v_mul_f32_e32 v17, v79, v69
	v_mov_b32_e32 v66, v242
	v_mov_b32_e32 v67, v243
	v_mov_b32_e32 v68, v244
	v_mov_b32_e32 v69, v245
	s_load_dwordx2 s[10:11], s[0:1], 0x128
	v_mul_f32_e32 v17, v14, v17
	v_cvt_pk_bf16_f32 v22, v0, v22
	v_cvt_pk_bf16_f32 v23, v23, v25
	s_waitcnt lgkmcnt(0)
	s_add_u32 s12, s10, s6
	s_addc_u32 s13, s11, s7
	s_add_u32 s12, s12, s33
	s_addc_u32 s13, s13, 0
	s_and_b64 vcc, exec, s[8:9]
	s_waitcnt vmcnt(0)
	v_mul_f32_e32 v14, v79, v66
	v_add_u32_e32 v66, s40, v165
	v_mul_f32_e32 v14, v21, v14
	v_mul_f32_e32 v21, v79, v67
	v_ashrrev_i32_e32 v67, 31, v66
	v_lshlrev_b64 v[66:67], 12, v[66:67]
	v_lshl_add_u64 v[66:67], s[12:13], 0, v[66:67]
	v_lshl_add_u64 v[66:67], v[66:67], 0, v[166:167]
	global_store_dwordx2 v[66:67], v[22:23], off
	v_cvt_pk_bf16_f32 v22, v24, v26
	v_cvt_pk_bf16_f32 v23, v27, v29
	global_store_dwordx2 v[66:67], v[22:23], off offset:16
	v_cvt_pk_bf16_f32 v22, v28, v30
	v_cvt_pk_bf16_f32 v23, v31, v33
	global_store_dwordx2 v[66:67], v[22:23], off offset:32
	v_cvt_pk_bf16_f32 v22, v32, v34
	v_cvt_pk_bf16_f32 v23, v35, v37
	global_store_dwordx2 v[66:67], v[22:23], off offset:48
	v_cvt_pk_bf16_f32 v22, v36, v38
	v_cvt_pk_bf16_f32 v23, v39, v41
	global_store_dwordx2 v[66:67], v[22:23], off offset:64
	v_cvt_pk_bf16_f32 v22, v40, v42
	v_cvt_pk_bf16_f32 v23, v43, v45
	global_store_dwordx2 v[66:67], v[22:23], off offset:80
	v_cvt_pk_bf16_f32 v22, v44, v46
	v_cvt_pk_bf16_f32 v23, v47, v49
	global_store_dwordx2 v[66:67], v[22:23], off offset:96
	v_cvt_pk_bf16_f32 v22, v48, v50
	v_cvt_pk_bf16_f32 v23, v51, v53
	global_store_dwordx2 v[66:67], v[22:23], off offset:112
	v_cvt_pk_bf16_f32 v22, v52, v54
	v_cvt_pk_bf16_f32 v23, v55, v57
	global_store_dwordx2 v[66:67], v[22:23], off offset:128
	v_cvt_pk_bf16_f32 v22, v56, v58
	v_cvt_pk_bf16_f32 v23, v59, v61
	global_store_dwordx2 v[66:67], v[22:23], off offset:144
	v_cvt_pk_bf16_f32 v22, v60, v62
	v_cvt_pk_bf16_f32 v23, v63, v64
	global_store_dwordx2 v[66:67], v[22:23], off offset:160
	v_cvt_pk_bf16_f32 v22, v5, v3
	v_cvt_pk_bf16_f32 v23, v4, v65
	global_store_dwordx2 v[66:67], v[22:23], off offset:176
	v_cvt_pk_bf16_f32 v2, v2, v7
	v_cvt_pk_bf16_f32 v3, v8, v9
	v_mul_f32_e32 v19, v19, v21
	v_mul_f32_e32 v21, v79, v68
	global_store_dwordx2 v[66:67], v[2:3], off offset:192
	v_cvt_pk_bf16_f32 v2, v6, v11
	v_cvt_pk_bf16_f32 v3, v12, v13
	v_mul_f32_e32 v20, v20, v21
	v_mul_f32_e32 v21, v79, v69
	global_store_dwordx2 v[66:67], v[2:3], off offset:208
	v_cvt_pk_bf16_f32 v2, v10, v15
	v_cvt_pk_bf16_f32 v3, v16, v17
	s_mov_b64 s[12:13], 0
	v_mul_f32_e32 v18, v18, v21
	global_store_dwordx2 v[66:67], v[2:3], off offset:224
	v_cvt_pk_bf16_f32 v2, v14, v19
	v_cvt_pk_bf16_f32 v3, v20, v18
	global_store_dwordx2 v[66:67], v[2:3], off offset:240
	s_cbranch_vccnz .LBB0_94
